# step20: nt (non-temporal) policy on the 2x545MB bf16 intermediate stores of proj0 (R/K/V/Z) and proj1 (K/V/Q/Z copies), on top of step19
# speedup vs baseline: 1.0314x; 1.0231x over previous
.LBB0_492:
	s_add_i32 s20, s31, 4
	s_min_u32 s45, s20, 31
	s_lshl_b32 s20, s45, 6
	v_lshl_add_u64 v[150:151], v[186:187], 0, s[20:21]
	global_load_dwordx4 v[166:169], v[150:151], off
	global_load_dwordx4 v[158:161], v[150:151], off offset:2048
	v_lshl_add_u64 v[150:151], v[188:189], 0, s[20:21]
	v_lshl_add_u64 v[154:155], v[190:191], 0, s[20:21]
	global_load_dwordx4 v[162:165], v[150:151], off
	s_nop 0
	global_load_dwordx4 v[150:153], v[154:155], off
	s_nop 0
	global_load_dwordx4 v[154:157], v[154:155], off offset:2048
	s_add_i32 s31, s31, 2
	v_lshl_or_b32 v246, s30, 15, v196
	v_add3_u32 v250, v246, v198, v199
	v_add3_u32 v251, v246, v200, v199
	ds_read_b128 v[230:233], v250 offset:16384
	ds_read_b128 v[234:237], v250 offset:17408
	ds_read_b128 v[238:241], v250 offset:18432
	ds_read_b128 v[242:245], v250 offset:19456
	ds_read_b128 v[246:249], v251
	s_waitcnt lgkmcnt(0)
	v_mfma_f32_16x16x32_bf16 v[146:149], v[230:233], v[246:249], v[146:149]
	v_mfma_f32_16x16x32_bf16 v[142:145], v[234:237], v[246:249], v[142:145]
	v_mfma_f32_16x16x32_bf16 v[138:141], v[238:241], v[246:249], v[138:141]
	v_mfma_f32_16x16x32_bf16 v[134:137], v[242:245], v[246:249], v[134:137]
	ds_read_b128 v[246:249], v251 offset:1024
	s_waitcnt lgkmcnt(0)
	v_mfma_f32_16x16x32_bf16 v[130:133], v[230:233], v[246:249], v[130:133]
	v_mfma_f32_16x16x32_bf16 v[126:129], v[234:237], v[246:249], v[126:129]
	v_mfma_f32_16x16x32_bf16 v[122:125], v[238:241], v[246:249], v[122:125]
	v_mfma_f32_16x16x32_bf16 v[118:121], v[242:245], v[246:249], v[118:121]
	ds_read_b128 v[246:249], v251 offset:2048
	s_waitcnt lgkmcnt(0)
	v_mfma_f32_16x16x32_bf16 v[114:117], v[230:233], v[246:249], v[114:117]
	v_mfma_f32_16x16x32_bf16 v[110:113], v[234:237], v[246:249], v[110:113]
	v_mfma_f32_16x16x32_bf16 v[106:109], v[238:241], v[246:249], v[106:109]
	v_mfma_f32_16x16x32_bf16 v[102:105], v[242:245], v[246:249], v[102:105]
	ds_read_b128 v[246:249], v251 offset:3072
	s_waitcnt lgkmcnt(0)
	v_mfma_f32_16x16x32_bf16 v[98:101], v[230:233], v[246:249], v[98:101]
	v_mfma_f32_16x16x32_bf16 v[94:97], v[234:237], v[246:249], v[94:97]
	v_mfma_f32_16x16x32_bf16 v[90:93], v[238:241], v[246:249], v[90:93]
	v_mfma_f32_16x16x32_bf16 v[82:85], v[242:245], v[246:249], v[82:85]
	ds_read_b128 v[230:233], v170
	ds_read_b128 v[234:237], v170 offset:16
	s_waitcnt vmcnt(9)
	v_lshlrev_b32_e32 v238, 16, v14
	v_and_b32_e32 v239, 0xffff0000, v14
	v_lshlrev_b32_e32 v240, 16, v15
	v_and_b32_e32 v241, 0xffff0000, v15
	s_waitcnt vmcnt(7)
	v_lshlrev_b32_e32 v14, 16, v18
	v_and_b32_e32 v15, 0xffff0000, v18
	v_sub_f32_e32 v14, v14, v238
	v_sub_f32_e32 v15, v15, v239
	v_lshlrev_b32_e32 v242, 16, v16
	v_and_b32_e32 v243, 0xffff0000, v16
	v_lshlrev_b32_e32 v244, 16, v17
	v_and_b32_e32 v245, 0xffff0000, v17
	v_lshlrev_b32_e32 v16, 16, v19
	v_and_b32_e32 v17, 0xffff0000, v19
	s_waitcnt lgkmcnt(1)
	v_fma_f32 v14, v14, v230, v238
	v_fma_f32 v15, v15, v231, v239
	v_cvt_pk_bf16_f32 v14, v14, v15
	v_sub_f32_e32 v15, v16, v240
	v_sub_f32_e32 v16, v17, v241
	v_lshlrev_b32_e32 v18, 16, v20
	v_and_b32_e32 v19, 0xffff0000, v20
	v_fma_f32 v15, v15, v232, v240
	v_fma_f32 v16, v16, v233, v241
	v_cvt_pk_bf16_f32 v15, v15, v16
	v_sub_f32_e32 v16, v18, v242
	v_sub_f32_e32 v17, v19, v243
	v_lshlrev_b32_e32 v20, 16, v21
	v_and_b32_e32 v21, 0xffff0000, v21
	s_waitcnt lgkmcnt(0)
	v_fma_f32 v16, v16, v234, v242
	v_fma_f32 v17, v17, v235, v243
	v_cvt_pk_bf16_f32 v16, v16, v17
	v_sub_f32_e32 v17, v20, v244
	v_sub_f32_e32 v18, v21, v245
	s_lshl_b32 s30, s7, 15
	v_fma_f32 v17, v17, v236, v244
	v_fma_f32 v18, v18, v237, v245
	v_cvt_pk_bf16_f32 v17, v17, v18
	v_or_b32_e32 v18, s30, v193
	ds_write_b128 v18, v[14:17]
	v_lshlrev_b32_e32 v14, 16, v10
	v_and_b32_e32 v10, 0xffff0000, v10
	v_sub_f32_e32 v19, v238, v14
	v_fmac_f32_e32 v14, v19, v230
	v_sub_f32_e32 v19, v239, v10
	v_lshlrev_b32_e32 v15, 16, v11
	v_fmac_f32_e32 v10, v19, v231
	v_and_b32_e32 v11, 0xffff0000, v11
	v_cvt_pk_bf16_f32 v10, v14, v10
	v_sub_f32_e32 v14, v240, v15
	v_lshlrev_b32_e32 v16, 16, v12
	v_fmac_f32_e32 v15, v14, v232
	v_sub_f32_e32 v14, v241, v11
	v_and_b32_e32 v12, 0xffff0000, v12
	v_fmac_f32_e32 v11, v14, v233
	v_sub_f32_e32 v14, v242, v16
	v_lshlrev_b32_e32 v17, 16, v13
	v_fmac_f32_e32 v16, v14, v234
	v_sub_f32_e32 v14, v243, v12
	v_and_b32_e32 v13, 0xffff0000, v13
	v_fmac_f32_e32 v12, v14, v235
	v_sub_f32_e32 v14, v244, v17
	v_fmac_f32_e32 v17, v14, v236
	v_sub_f32_e32 v14, v245, v13
	v_fmac_f32_e32 v13, v14, v237
	v_cvt_pk_bf16_f32 v11, v15, v11
	v_cvt_pk_bf16_f32 v12, v16, v12
	v_cvt_pk_bf16_f32 v13, v17, v13
	v_add_u32_e32 v14, s30, v194
	ds_write_b128 v14, v[10:13]
	s_waitcnt vmcnt(6)
	ds_write_b128 v18, v[2:5] offset:16384
	s_waitcnt vmcnt(5)
	ds_write_b128 v14, v[6:9] offset:16384
	ds_read_b128 v[2:5], v250 offset:16384
	ds_read_b128 v[6:9], v250 offset:17408
	ds_read_b128 v[10:13], v251 offset:4096
	ds_read_b128 v[14:17], v251 offset:5120
	ds_read_b128 v[230:233], v250 offset:18432
	ds_read_b128 v[234:237], v250 offset:19456
	s_min_u32 s20, s31, 28
	s_waitcnt lgkmcnt(3)
	v_mfma_f32_16x16x32_bf16 v[86:89], v[2:5], v[10:13], v[86:89]
	s_lshl_b32 s20, s20, 6
	v_mfma_f32_16x16x32_bf16 v[78:81], v[6:9], v[10:13], v[78:81]
	s_waitcnt lgkmcnt(1)
	v_mfma_f32_16x16x32_bf16 v[74:77], v[230:233], v[10:13], v[74:77]
	s_waitcnt lgkmcnt(0)
	v_mfma_f32_16x16x32_bf16 v[70:73], v[234:237], v[10:13], v[70:73]
	ds_read_b128 v[10:13], v251 offset:6144
	ds_read_b128 v[238:241], v251 offset:7168
	s_waitcnt lgkmcnt(0)
	s_barrier
	v_mfma_f32_16x16x32_bf16 v[66:69], v[2:5], v[14:17], v[66:69]
	v_mfma_f32_16x16x32_bf16 v[46:49], v[2:5], v[10:13], v[46:49]
	v_mfma_f32_16x16x32_bf16 v[30:33], v[2:5], v[238:241], v[30:33]
	v_lshl_add_u64 v[2:3], v[186:187], 0, s[20:21]
	v_mfma_f32_16x16x32_bf16 v[62:65], v[6:9], v[14:17], v[62:65]
	v_mfma_f32_16x16x32_bf16 v[54:57], v[230:233], v[14:17], v[54:57]
	v_mfma_f32_16x16x32_bf16 v[50:53], v[234:237], v[14:17], v[50:53]
	v_mfma_f32_16x16x32_bf16 v[42:45], v[6:9], v[10:13], v[42:45]
	v_mfma_f32_16x16x32_bf16 v[38:41], v[230:233], v[10:13], v[38:41]
	v_mfma_f32_16x16x32_bf16 v[34:37], v[234:237], v[10:13], v[34:37]
	global_load_dwordx4 v[14:17], v[2:3], off offset:192
	global_load_dwordx4 v[10:13], v[2:3], off offset:2240
	v_lshl_add_u64 v[2:3], v[188:189], 0, s[20:21]
	global_load_dwordx4 v[18:21], v[2:3], off offset:192
	v_mfma_f32_16x16x32_bf16 v[26:29], v[6:9], v[238:241], v[26:29]
	v_lshl_add_u64 v[6:7], v[190:191], 0, s[20:21]
	global_load_dwordx4 v[2:5], v[6:7], off offset:192
	s_nop 0
	global_load_dwordx4 v[6:9], v[6:7], off offset:2240
	s_add_i32 s20, s7, 1
	v_mfma_f32_16x16x32_bf16 v[22:25], v[230:233], v[238:241], v[22:25]
	v_mfma_f32_16x16x32_bf16 v[58:61], v[234:237], v[238:241], v[58:61]
	v_or_b32_e32 v246, s30, v196
	v_add3_u32 v250, v246, v198, v199
	v_add3_u32 v251, v246, v200, v199
	ds_read_b128 v[230:233], v250 offset:16384
	ds_read_b128 v[234:237], v250 offset:17408
	ds_read_b128 v[238:241], v250 offset:18432
	ds_read_b128 v[242:245], v250 offset:19456
	ds_read_b128 v[246:249], v251
	s_cmp_lg_u32 s7, 2
	s_cselect_b32 s30, s20, 0
	s_waitcnt lgkmcnt(0)
	v_mfma_f32_16x16x32_bf16 v[146:149], v[230:233], v[246:249], v[146:149]
	v_mfma_f32_16x16x32_bf16 v[142:145], v[234:237], v[246:249], v[142:145]
	v_mfma_f32_16x16x32_bf16 v[138:141], v[238:241], v[246:249], v[138:141]
	v_mfma_f32_16x16x32_bf16 v[134:137], v[242:245], v[246:249], v[134:137]
	ds_read_b128 v[246:249], v251 offset:1024
	s_waitcnt lgkmcnt(0)
	v_mfma_f32_16x16x32_bf16 v[130:133], v[230:233], v[246:249], v[130:133]
	v_mfma_f32_16x16x32_bf16 v[126:129], v[234:237], v[246:249], v[126:129]
	v_mfma_f32_16x16x32_bf16 v[122:125], v[238:241], v[246:249], v[122:125]
	v_mfma_f32_16x16x32_bf16 v[118:121], v[242:245], v[246:249], v[118:121]
	ds_read_b128 v[246:249], v251 offset:2048
	s_waitcnt lgkmcnt(0)
	v_mfma_f32_16x16x32_bf16 v[114:117], v[230:233], v[246:249], v[114:117]
	v_mfma_f32_16x16x32_bf16 v[110:113], v[234:237], v[246:249], v[110:113]
	v_mfma_f32_16x16x32_bf16 v[106:109], v[238:241], v[246:249], v[106:109]
	v_mfma_f32_16x16x32_bf16 v[102:105], v[242:245], v[246:249], v[102:105]
	ds_read_b128 v[246:249], v251 offset:3072
	s_waitcnt lgkmcnt(0)
	v_mfma_f32_16x16x32_bf16 v[98:101], v[230:233], v[246:249], v[98:101]
	v_mfma_f32_16x16x32_bf16 v[94:97], v[234:237], v[246:249], v[94:97]
	v_mfma_f32_16x16x32_bf16 v[90:93], v[238:241], v[246:249], v[90:93]
	v_mfma_f32_16x16x32_bf16 v[82:85], v[242:245], v[246:249], v[82:85]
	v_lshl_add_u32 v234, s45, 7, v197
	ds_read_b128 v[230:233], v234
	ds_read_b128 v[234:237], v234 offset:16
	s_waitcnt vmcnt(9)
	v_lshlrev_b32_e32 v238, 16, v166
	v_and_b32_e32 v166, 0xffff0000, v166
	s_waitcnt vmcnt(7)
	v_lshlrev_b32_e32 v242, 16, v162
	v_and_b32_e32 v162, 0xffff0000, v162
	v_sub_f32_e32 v242, v242, v238
	v_sub_f32_e32 v162, v162, v166
	v_lshlrev_b32_e32 v239, 16, v167
	v_and_b32_e32 v167, 0xffff0000, v167
	v_lshlrev_b32_e32 v243, 16, v163
	v_and_b32_e32 v163, 0xffff0000, v163
	s_waitcnt lgkmcnt(1)
	v_fma_f32 v242, v242, v230, v238
	v_fma_f32 v162, v162, v231, v166
	v_cvt_pk_bf16_f32 v162, v242, v162
	v_sub_f32_e32 v242, v243, v239
	v_sub_f32_e32 v163, v163, v167
	v_lshlrev_b32_e32 v240, 16, v168
	v_and_b32_e32 v168, 0xffff0000, v168
	v_lshlrev_b32_e32 v244, 16, v164
	v_and_b32_e32 v164, 0xffff0000, v164
	v_fma_f32 v242, v242, v232, v239
	v_fma_f32 v163, v163, v233, v167
	v_cvt_pk_bf16_f32 v163, v242, v163
	v_sub_f32_e32 v242, v244, v240
	v_sub_f32_e32 v164, v164, v168
	v_lshlrev_b32_e32 v241, 16, v169
	v_and_b32_e32 v169, 0xffff0000, v169
	v_lshlrev_b32_e32 v245, 16, v165
	v_and_b32_e32 v165, 0xffff0000, v165
	s_waitcnt lgkmcnt(0)
	v_fma_f32 v242, v242, v234, v240
	v_fma_f32 v164, v164, v235, v168
	v_cvt_pk_bf16_f32 v164, v242, v164
	v_sub_f32_e32 v242, v245, v241
	v_sub_f32_e32 v165, v165, v169
	s_lshl_b32 s7, s30, 15
	v_fma_f32 v242, v242, v236, v241
	v_fma_f32 v165, v165, v237, v169
	v_cvt_pk_bf16_f32 v165, v242, v165
	v_or_b32_e32 v242, s7, v193
	ds_write_b128 v242, v[162:165]
	v_lshlrev_b32_e32 v162, 16, v158
	v_and_b32_e32 v158, 0xffff0000, v158
	v_sub_f32_e32 v238, v238, v162
	v_sub_f32_e32 v166, v166, v158
	v_lshlrev_b32_e32 v163, 16, v159
	v_fmac_f32_e32 v162, v238, v230
	v_fmac_f32_e32 v158, v166, v231
	v_and_b32_e32 v159, 0xffff0000, v159
	v_cvt_pk_bf16_f32 v158, v162, v158
	v_sub_f32_e32 v162, v239, v163
	v_lshlrev_b32_e32 v164, 16, v160
	v_fmac_f32_e32 v163, v162, v232
	v_sub_f32_e32 v162, v167, v159
	v_and_b32_e32 v160, 0xffff0000, v160
	v_fmac_f32_e32 v159, v162, v233
	v_sub_f32_e32 v162, v240, v164
	v_lshlrev_b32_e32 v165, 16, v161
	v_fmac_f32_e32 v164, v162, v234
	v_sub_f32_e32 v162, v168, v160
	v_and_b32_e32 v161, 0xffff0000, v161
	v_fmac_f32_e32 v160, v162, v235
	v_sub_f32_e32 v162, v241, v165
	v_fmac_f32_e32 v165, v162, v236
	v_sub_f32_e32 v162, v169, v161
	v_fmac_f32_e32 v161, v162, v237
	v_cvt_pk_bf16_f32 v159, v163, v159
	v_cvt_pk_bf16_f32 v160, v164, v160
	v_cvt_pk_bf16_f32 v161, v165, v161
	v_add_u32_e32 v162, s7, v194
	ds_write_b128 v162, v[158:161]
	s_waitcnt vmcnt(6)
	ds_write_b128 v242, v[150:153] offset:16384
	s_waitcnt vmcnt(5)
	ds_write_b128 v162, v[154:157] offset:16384
	ds_read_b128 v[150:153], v250 offset:16384
	ds_read_b128 v[154:157], v250 offset:17408
	ds_read_b128 v[158:161], v251 offset:4096
	ds_read_b128 v[162:165], v251 offset:5120
	ds_read_b128 v[166:169], v250 offset:18432
	ds_read_b128 v[230:233], v250 offset:19456
	s_add_i32 s7, s30, 1
	s_waitcnt lgkmcnt(3)
	v_mfma_f32_16x16x32_bf16 v[86:89], v[150:153], v[158:161], v[86:89]
	s_cmp_lg_u32 s30, 2
	s_cselect_b32 s7, s7, 0
	v_add_u32_e32 v170, 0x100, v170
	v_mfma_f32_16x16x32_bf16 v[78:81], v[154:157], v[158:161], v[78:81]
	s_cmp_lt_u32 s31, 30
	s_waitcnt lgkmcnt(1)
	v_mfma_f32_16x16x32_bf16 v[74:77], v[166:169], v[158:161], v[74:77]
	s_waitcnt lgkmcnt(0)
	v_mfma_f32_16x16x32_bf16 v[70:73], v[230:233], v[158:161], v[70:73]
	v_mfma_f32_16x16x32_bf16 v[66:69], v[150:153], v[162:165], v[66:69]
	v_mfma_f32_16x16x32_bf16 v[62:65], v[154:157], v[162:165], v[62:65]
	v_mfma_f32_16x16x32_bf16 v[54:57], v[166:169], v[162:165], v[54:57]
	v_mfma_f32_16x16x32_bf16 v[50:53], v[230:233], v[162:165], v[50:53]
	ds_read_b128 v[158:161], v251 offset:6144
	ds_read_b128 v[162:165], v251 offset:7168
	s_waitcnt lgkmcnt(0)
	s_barrier
	v_mfma_f32_16x16x32_bf16 v[46:49], v[150:153], v[158:161], v[46:49]
	v_mfma_f32_16x16x32_bf16 v[42:45], v[154:157], v[158:161], v[42:45]
	v_mfma_f32_16x16x32_bf16 v[38:41], v[166:169], v[158:161], v[38:41]
	v_mfma_f32_16x16x32_bf16 v[34:37], v[230:233], v[158:161], v[34:37]
	v_mfma_f32_16x16x32_bf16 v[30:33], v[150:153], v[162:165], v[30:33]
	v_mfma_f32_16x16x32_bf16 v[26:29], v[154:157], v[162:165], v[26:29]
	v_mfma_f32_16x16x32_bf16 v[22:25], v[166:169], v[162:165], v[22:25]
	v_mfma_f32_16x16x32_bf16 v[58:61], v[230:233], v[162:165], v[58:61]
	s_cbranch_scc1 .LBB0_492
	s_waitcnt vmcnt(1)
	v_cvt_pk_bf16_f32 v2, v146, v147
	v_cvt_pk_bf16_f32 v3, v148, v149
	v_cvt_pk_bf16_f32 v4, v142, v143
	v_cvt_pk_bf16_f32 v5, v144, v145
	ds_write2_b64 v201, v[2:3], v[4:5] offset1:4
	v_cvt_pk_bf16_f32 v2, v138, v139
	v_cvt_pk_bf16_f32 v3, v140, v141
	v_cvt_pk_bf16_f32 v4, v134, v135
	v_cvt_pk_bf16_f32 v5, v136, v137
	ds_write2_b64 v201, v[2:3], v[4:5] offset0:8 offset1:12
	v_cvt_pk_bf16_f32 v2, v130, v131
	v_cvt_pk_bf16_f32 v3, v132, v133
	v_cvt_pk_bf16_f32 v4, v126, v127
	v_cvt_pk_bf16_f32 v5, v128, v129
	s_waitcnt vmcnt(0)
	v_add_u32_e32 v6, 0x2000, v201
	ds_write2_b64 v6, v[2:3], v[4:5] offset0:32 offset1:36
	v_cvt_pk_bf16_f32 v2, v122, v123
	v_cvt_pk_bf16_f32 v3, v124, v125
	v_cvt_pk_bf16_f32 v4, v118, v119
	v_cvt_pk_bf16_f32 v5, v120, v121
	ds_write2_b64 v6, v[2:3], v[4:5] offset0:40 offset1:44
	v_cvt_pk_bf16_f32 v2, v114, v115
	v_cvt_pk_bf16_f32 v3, v116, v117
	v_cvt_pk_bf16_f32 v4, v110, v111
	v_cvt_pk_bf16_f32 v5, v112, v113
	v_add_u32_e32 v6, 0x4000, v201
	ds_write2_b64 v6, v[2:3], v[4:5] offset0:64 offset1:68
	v_cvt_pk_bf16_f32 v2, v106, v107
	v_cvt_pk_bf16_f32 v3, v108, v109
	v_cvt_pk_bf16_f32 v4, v102, v103
	v_cvt_pk_bf16_f32 v5, v104, v105
	ds_write2_b64 v6, v[2:3], v[4:5] offset0:72 offset1:76
	v_cvt_pk_bf16_f32 v2, v98, v99
	v_cvt_pk_bf16_f32 v3, v100, v101
	v_cvt_pk_bf16_f32 v4, v94, v95
	v_cvt_pk_bf16_f32 v5, v96, v97
	v_add_u32_e32 v6, 0x6000, v201
	ds_write2_b64 v6, v[2:3], v[4:5] offset0:96 offset1:100
	v_cvt_pk_bf16_f32 v2, v90, v91
	v_cvt_pk_bf16_f32 v3, v92, v93
	v_cvt_pk_bf16_f32 v4, v82, v83
	v_cvt_pk_bf16_f32 v5, v84, v85
	ds_write2_b64 v6, v[2:3], v[4:5] offset0:104 offset1:108
	v_cvt_pk_bf16_f32 v2, v86, v87
	v_cvt_pk_bf16_f32 v3, v88, v89
	v_cvt_pk_bf16_f32 v4, v78, v79
	v_cvt_pk_bf16_f32 v5, v80, v81
	v_add_u32_e32 v6, 0x8000, v201
	ds_write2_b64 v6, v[2:3], v[4:5] offset0:128 offset1:132
	v_cvt_pk_bf16_f32 v2, v74, v75
	v_cvt_pk_bf16_f32 v3, v76, v77
	v_cvt_pk_bf16_f32 v4, v70, v71
	v_cvt_pk_bf16_f32 v5, v72, v73
	ds_write2_b64 v6, v[2:3], v[4:5] offset0:136 offset1:140
	v_cvt_pk_bf16_f32 v2, v66, v67
	v_cvt_pk_bf16_f32 v3, v68, v69
	v_cvt_pk_bf16_f32 v4, v62, v63
	v_cvt_pk_bf16_f32 v5, v64, v65
	v_add_u32_e32 v6, 0xa000, v201
	ds_write2_b64 v6, v[2:3], v[4:5] offset0:160 offset1:164
	v_cvt_pk_bf16_f32 v2, v54, v55
	v_cvt_pk_bf16_f32 v3, v56, v57
	v_cvt_pk_bf16_f32 v4, v50, v51
	v_cvt_pk_bf16_f32 v5, v52, v53
	ds_write2_b64 v6, v[2:3], v[4:5] offset0:168 offset1:172
	v_cvt_pk_bf16_f32 v2, v46, v47
	v_cvt_pk_bf16_f32 v3, v48, v49
	v_cvt_pk_bf16_f32 v4, v42, v43
	v_cvt_pk_bf16_f32 v5, v44, v45
	v_add_u32_e32 v6, 0xc000, v201
	ds_write2_b64 v6, v[2:3], v[4:5] offset0:192 offset1:196
	v_cvt_pk_bf16_f32 v2, v38, v39
	v_cvt_pk_bf16_f32 v3, v40, v41
	v_cvt_pk_bf16_f32 v4, v34, v35
	v_cvt_pk_bf16_f32 v5, v36, v37
	ds_write2_b64 v6, v[2:3], v[4:5] offset0:200 offset1:204
	v_cvt_pk_bf16_f32 v2, v30, v31
	v_cvt_pk_bf16_f32 v3, v32, v33
	v_cvt_pk_bf16_f32 v4, v26, v27
	v_cvt_pk_bf16_f32 v5, v28, v29
	v_add_u32_e32 v6, 0xe000, v201
	ds_write2_b64 v6, v[2:3], v[4:5] offset0:224 offset1:228
	v_cvt_pk_bf16_f32 v2, v22, v23
	v_cvt_pk_bf16_f32 v3, v24, v25
	v_cvt_pk_bf16_f32 v4, v58, v59
	v_cvt_pk_bf16_f32 v5, v60, v61
	ds_write2_b64 v6, v[2:3], v[4:5] offset0:232 offset1:236
	s_waitcnt lgkmcnt(0)
	s_barrier
	ds_read_b128 v[2:5], v218
	s_sub_i32 s6, s6, s44
	v_or_b32_e32 v6, s26, v202
	s_ashr_i32 s7, s6, 31
	v_ashrrev_i32_e32 v7, 31, v6
	v_lshl_add_u64 v[14:15], s[6:7], 1, v[182:183]
	v_lshlrev_b64 v[6:7], 12, v[6:7]
	v_lshl_add_u64 v[10:11], v[14:15], 0, v[6:7]
	ds_read_b128 v[6:9], v218 offset:16896
	s_waitcnt lgkmcnt(1)
	global_store_dwordx4 v[10:11], v[2:5], off nt
	ds_read_b128 v[2:5], v219
	v_or_b32_e32 v10, s26, v203
	v_ashrrev_i32_e32 v11, 31, v10
	v_lshlrev_b64 v[10:11], 12, v[10:11]
	v_lshl_add_u64 v[16:17], v[14:15], 0, v[10:11]
	ds_read_b128 v[10:13], v220
	s_waitcnt lgkmcnt(1)
	global_store_dwordx4 v[16:17], v[2:5], off nt
	s_nop 1
	v_or_b32_e32 v2, 32, v202
	v_or_b32_e32 v2, s26, v2
	v_ashrrev_i32_e32 v3, 31, v2
	v_lshlrev_b64 v[2:3], 12, v[2:3]
	v_lshl_add_u64 v[2:3], v[14:15], 0, v[2:3]
	global_store_dwordx4 v[2:3], v[6:9], off nt
	v_or_b32_e32 v2, s26, v204
	v_ashrrev_i32_e32 v3, 31, v2
	v_lshlrev_b64 v[2:3], 12, v[2:3]
	v_lshl_add_u64 v[2:3], v[14:15], 0, v[2:3]
	s_waitcnt lgkmcnt(0)
	global_store_dwordx4 v[2:3], v[10:13], off nt
	ds_read_b128 v[2:5], v218 offset:33792
	v_or_b32_e32 v6, s26, v205
	v_ashrrev_i32_e32 v7, 31, v6
	v_lshlrev_b64 v[6:7], 12, v[6:7]
	v_lshl_add_u64 v[10:11], v[14:15], 0, v[6:7]
	ds_read_b128 v[6:9], v218 offset:50688
	s_waitcnt lgkmcnt(1)
	global_store_dwordx4 v[10:11], v[2:5], off nt
	ds_read_b128 v[2:5], v221
	v_or_b32_e32 v10, s26, v206
	v_ashrrev_i32_e32 v11, 31, v10
	v_lshlrev_b64 v[10:11], 12, v[10:11]
	v_lshl_add_u64 v[16:17], v[14:15], 0, v[10:11]
	ds_read_b128 v[10:13], v222
	s_waitcnt lgkmcnt(1)
	global_store_dwordx4 v[16:17], v[2:5], off nt
	s_nop 1
	v_or_b32_e32 v2, s26, v207
	v_ashrrev_i32_e32 v3, 31, v2
	v_lshlrev_b64 v[2:3], 12, v[2:3]
	v_lshl_add_u64 v[2:3], v[14:15], 0, v[2:3]
	global_store_dwordx4 v[2:3], v[6:9], off nt
	v_or_b32_e32 v2, s26, v208
	v_ashrrev_i32_e32 v3, 31, v2
	v_lshlrev_b64 v[2:3], 12, v[2:3]
	v_lshl_add_u64 v[2:3], v[14:15], 0, v[2:3]
	s_waitcnt lgkmcnt(0)
	global_store_dwordx4 v[2:3], v[10:13], off nt
	ds_read_b128 v[2:5], v223
	v_or_b32_e32 v6, s26, v209
	v_ashrrev_i32_e32 v7, 31, v6
	v_lshlrev_b64 v[6:7], 12, v[6:7]
	v_lshl_add_u64 v[10:11], v[14:15], 0, v[6:7]
	ds_read_b128 v[6:9], v223 offset:16896
	s_waitcnt lgkmcnt(1)
	global_store_dwordx4 v[10:11], v[2:5], off nt
	ds_read_b128 v[2:5], v224
	v_or_b32_e32 v10, s26, v210
	v_ashrrev_i32_e32 v11, 31, v10
	v_lshlrev_b64 v[10:11], 12, v[10:11]
	v_lshl_add_u64 v[16:17], v[14:15], 0, v[10:11]
	ds_read_b128 v[10:13], v225
	s_waitcnt lgkmcnt(1)
	global_store_dwordx4 v[16:17], v[2:5], off nt
	s_nop 1
	v_or_b32_e32 v2, s26, v211
	v_ashrrev_i32_e32 v3, 31, v2
	v_lshlrev_b64 v[2:3], 12, v[2:3]
	v_lshl_add_u64 v[2:3], v[14:15], 0, v[2:3]
	global_store_dwordx4 v[2:3], v[6:9], off nt
	v_or_b32_e32 v2, s26, v212
	v_ashrrev_i32_e32 v3, 31, v2
	v_lshlrev_b64 v[2:3], 12, v[2:3]
	v_lshl_add_u64 v[2:3], v[14:15], 0, v[2:3]
	s_waitcnt lgkmcnt(0)
	global_store_dwordx4 v[2:3], v[10:13], off nt
	ds_read_b128 v[2:5], v223 offset:33792
	v_or_b32_e32 v6, s27, v213
	v_ashrrev_i32_e32 v7, 31, v6
	v_lshlrev_b64 v[6:7], 12, v[6:7]
	v_lshl_add_u64 v[10:11], v[14:15], 0, v[6:7]
	ds_read_b128 v[6:9], v223 offset:50688
	s_waitcnt lgkmcnt(1)
	global_store_dwordx4 v[10:11], v[2:5], off nt
	ds_read_b128 v[2:5], v226
	v_or_b32_e32 v10, s27, v214
	v_ashrrev_i32_e32 v11, 31, v10
	v_lshlrev_b64 v[10:11], 12, v[10:11]
	v_lshl_add_u64 v[16:17], v[14:15], 0, v[10:11]
	ds_read_b128 v[10:13], v227
	s_waitcnt lgkmcnt(1)
	global_store_dwordx4 v[16:17], v[2:5], off nt
	s_nop 1
	v_or_b32_e32 v2, s27, v215
	v_ashrrev_i32_e32 v3, 31, v2
	v_lshlrev_b64 v[2:3], 12, v[2:3]
	v_lshl_add_u64 v[2:3], v[14:15], 0, v[2:3]
	global_store_dwordx4 v[2:3], v[6:9], off nt
	v_add_u32_e32 v2, s26, v216
	v_ashrrev_i32_e32 v3, 31, v2
	v_lshlrev_b64 v[2:3], 12, v[2:3]
	v_lshl_add_u64 v[2:3], v[14:15], 0, v[2:3]
	s_waitcnt lgkmcnt(0)
	global_store_dwordx4 v[2:3], v[10:13], off nt
	s_barrier
	s_barrier
	s_and_saveexec_b64 s[6:7], s[0:1]
	s_cbranch_execz .LBB0_482
	ds_write_b32 v217, v229
	s_branch .LBB0_482

.LBB0_816:
	ds_read_b128 v[138:141], v136
	ds_read_b128 v[142:145], v135
	ds_read_b128 v[218:221], v135 offset:16896
	ds_read_b128 v[222:225], v137
	v_add_u32_e32 v226, s6, v134
	v_add_u32_e32 v228, s6, v133
	v_add_u32_e32 v230, s6, v132
	v_ashrrev_i32_e32 v227, 31, v226
	v_add_u32_e32 v232, 32, v226
	s_add_i32 s6, s6, 64
	v_ashrrev_i32_e32 v229, 31, v228
	v_ashrrev_i32_e32 v231, 31, v230
	v_lshlrev_b64 v[226:227], 12, v[226:227]
	v_ashrrev_i32_e32 v233, 31, v232
	v_add_u32_e32 v137, 0x8400, v137
	v_add_u32_e32 v136, 0x8400, v136
	v_add_u32_e32 v135, 0x8400, v135
	s_cmpk_eq_i32 s6, 0x100
	v_lshlrev_b64 v[228:229], 12, v[228:229]
	v_lshlrev_b64 v[230:231], 12, v[230:231]
	v_lshl_add_u64 v[226:227], v[130:131], 0, v[226:227]
	v_lshlrev_b64 v[232:233], 12, v[232:233]
	v_lshl_add_u64 v[228:229], v[130:131], 0, v[228:229]
	v_lshl_add_u64 v[230:231], v[130:131], 0, v[230:231]
	v_lshl_add_u64 v[232:233], v[130:131], 0, v[232:233]
	s_waitcnt lgkmcnt(2)
	global_store_dwordx4 v[226:227], v[142:145], off nt
	global_store_dwordx4 v[228:229], v[138:141], off nt
	s_waitcnt lgkmcnt(1)
	global_store_dwordx4 v[232:233], v[218:221], off nt
	s_waitcnt lgkmcnt(0)
	global_store_dwordx4 v[230:231], v[222:225], off nt
	s_cbranch_scc0 .LBB0_816
	s_and_b64 vcc, exec, s[34:35]
	s_barrier
	s_cbranch_vccz .LBB0_955
	v_cndmask_b32_e64 v130, 0, 1, s[38:39]
	v_cmp_ne_u32_e64 s[6:7], 1, v130
	s_nop 1
	s_and_b64 vcc, exec, s[6:7]
	s_cbranch_vccnz .Lp1_nogain
	global_load_dwordx4 v[240:243], v[150:151], off
	global_load_dwordx4 v[244:247], v[150:151], off offset:64
	global_load_dwordx4 v[248:251], v[150:151], off offset:128
	s_waitcnt vmcnt(0)
